# loop-edge edit 2: always-false wave-uniform branch test before the attention DMA wait removed (plus the SCC branch at the loop head)
# baseline (speedup 1.0000x reference)
.LBB0_745:
.LBB0_746:
	s_waitcnt vmcnt(4)
